# SwiGLU epilogue (both FFN gate-up GEMMs) hand-scheduled: same arithmetic order, 8-wide stages, no hazard nops
# speedup vs baseline: 1.0135x; 1.0059x over previous
.LBB0_279:
	v_lshl_add_u32 v176, s6, 8, v203
	v_ashrrev_i32_e32 v177, 31, v176
	v_lshlrev_b64 v[76:77], 6, v[176:177]
	v_lshl_add_u64 v[76:77], v[160:161], 0, v[76:77]
	v_or_b32_e32 v184, 16, v176
	global_load_dwordx4 v[168:171], v[76:77], off
	v_ashrrev_i32_e32 v185, 31, v184
	v_lshlrev_b64 v[76:77], 6, v[184:185]
	v_lshl_add_u64 v[76:77], v[160:161], 0, v[76:77]
	global_load_dwordx4 v[208:211], v[76:77], off
	v_or_b32_e32 v182, 32, v176
	v_ashrrev_i32_e32 v183, 31, v182
	v_lshlrev_b64 v[76:77], 6, v[182:183]
	v_or_b32_e32 v180, 48, v176
	v_lshl_add_u64 v[76:77], v[160:161], 0, v[76:77]
	v_ashrrev_i32_e32 v181, 31, v180
	global_load_dwordx4 v[150:153], v[76:77], off
	v_lshlrev_b64 v[76:77], 6, v[180:181]
	v_add_u32_e32 v178, 0x80, v176
	v_lshl_add_u64 v[76:77], v[160:161], 0, v[76:77]
	v_ashrrev_i32_e32 v179, 31, v178
	global_load_dwordx4 v[146:149], v[76:77], off
	v_lshlrev_b64 v[76:77], 6, v[178:179]
	v_add_u32_e32 v174, 0x90, v176
	v_lshl_add_u64 v[76:77], v[160:161], 0, v[76:77]
	v_ashrrev_i32_e32 v175, 31, v174
	global_load_dwordx4 v[122:125], v[76:77], off
	v_lshlrev_b64 v[76:77], 6, v[174:175]
	v_add_u32_e32 v172, 0xa0, v176
	v_lshl_add_u64 v[76:77], v[160:161], 0, v[76:77]
	v_ashrrev_i32_e32 v173, 31, v172
	v_lshl_or_b32 v194, s7, 7, v205
	global_load_dwordx4 v[118:121], v[76:77], off
	v_lshlrev_b64 v[76:77], 6, v[172:173]
	v_add_u32_e32 v166, 0xb0, v176
	v_ashrrev_i32_e32 v195, 31, v194
	v_lshl_add_u64 v[76:77], v[160:161], 0, v[76:77]
	v_ashrrev_i32_e32 v167, 31, v166
	v_and_b32_e32 v173, 64, v245
	global_load_dwordx4 v[80:83], v[76:77], off
	v_lshlrev_b64 v[76:77], 6, v[166:167]
	v_xor_b32_e32 v167, 16, v245
	v_add_u32_e32 v175, 64, v173
	v_cmp_lt_i32_e32 vcc, v167, v175
	s_mov_b32 s22, 0x3a800000
	v_lshl_add_u64 v[76:77], v[160:161], 0, v[76:77]
	v_cndmask_b32_e32 v167, v245, v167, vcc
	v_lshlrev_b32_e32 v173, 2, v167
	v_xor_b32_e32 v167, 32, v245
	v_cmp_lt_i32_e32 vcc, v167, v175
	global_load_dwordx4 v[76:79], v[76:77], off
	v_readlane_b32 s50, v255, 34
	v_cndmask_b32_e32 v167, v245, v167, vcc
	v_lshlrev_b32_e32 v167, 2, v167
	v_readlane_b32 s62, v255, 36
	v_readlane_b32 s51, v255, 35
	v_readlane_b32 s63, v255, 37
	s_waitcnt vmcnt(0)
	v_add_f32_e32 v169, v169, v168
	v_add_f32_e32 v171, v170, v171
	v_add_f32_e32 v209, v209, v208
	v_add_f32_e32 v211, v210, v211
	v_add_f32_e32 v151, v151, v150
	v_add_f32_e32 v153, v152, v153
	v_add_f32_e32 v147, v147, v146
	v_add_f32_e32 v149, v148, v149
	v_add_f32_e32 v123, v123, v122
	v_add_f32_e32 v125, v124, v125
	v_add_f32_e32 v119, v119, v118
	v_add_f32_e32 v121, v120, v121
	v_add_f32_e32 v81, v81, v80
	v_add_f32_e32 v83, v82, v83
	v_add_f32_e32 v77, v77, v76
	v_add_f32_e32 v79, v78, v79
	v_add_f32_e32 v168, v169, v171
	v_add_f32_e32 v208, v209, v211
	v_add_f32_e32 v150, v151, v153
	v_add_f32_e32 v146, v147, v149
	v_add_f32_e32 v122, v123, v125
	v_add_f32_e32 v118, v119, v121
	v_add_f32_e32 v80, v81, v83
	v_add_f32_e32 v76, v77, v79
	ds_bpermute_b32 v169, v173, v168
	ds_bpermute_b32 v209, v173, v208
	ds_bpermute_b32 v151, v173, v150
	ds_bpermute_b32 v147, v173, v146
	ds_bpermute_b32 v123, v173, v122
	ds_bpermute_b32 v119, v173, v118
	ds_bpermute_b32 v81, v173, v80
	ds_bpermute_b32 v77, v173, v76
	v_lshlrev_b64 v[170:171], 1, v[194:195]
	v_lshl_add_u64 v[170:171], s[10:11], 0, v[170:171]
	s_waitcnt lgkmcnt(0)
	v_add_f32_e32 v168, v168, v169
	v_add_f32_e32 v208, v208, v209
	v_add_f32_e32 v150, v150, v151
	v_add_f32_e32 v146, v146, v147
	v_add_f32_e32 v122, v122, v123
	v_add_f32_e32 v118, v118, v119
	v_add_f32_e32 v80, v80, v81
	v_add_f32_e32 v76, v76, v77
	ds_bpermute_b32 v169, v167, v168
	ds_bpermute_b32 v209, v167, v208
	ds_bpermute_b32 v151, v167, v150
	ds_bpermute_b32 v147, v167, v146
	ds_bpermute_b32 v123, v167, v122
	ds_bpermute_b32 v119, v167, v118
	ds_bpermute_b32 v81, v167, v80
	ds_bpermute_b32 v77, v167, v76
	s_waitcnt lgkmcnt(0)
	v_add_f32_e32 v168, v168, v169
	v_add_f32_e32 v208, v208, v209
	v_add_f32_e32 v150, v150, v151
	v_add_f32_e32 v146, v146, v147
	v_add_f32_e32 v122, v122, v123
	v_add_f32_e32 v118, v118, v119
	v_add_f32_e32 v80, v80, v81
	v_add_f32_e32 v76, v76, v77
	v_mov_b32_e32 v78, 0x358637bd
	v_fma_f32 v168, v168, s22, v78
	v_fma_f32 v208, v208, s22, v78
	v_fma_f32 v150, v150, s22, v78
	v_fma_f32 v146, v146, s22, v78
	v_fma_f32 v122, v122, s22, v78
	v_fma_f32 v118, v118, s22, v78
	v_fma_f32 v80, v80, s22, v78
	v_fma_f32 v76, v76, s22, v78
	v_rsq_f32_e32 v168, v168
	v_rsq_f32_e32 v208, v208
	v_rsq_f32_e32 v150, v150
	v_rsq_f32_e32 v146, v146
	v_rsq_f32_e32 v122, v122
	v_rsq_f32_e32 v118, v118
	v_rsq_f32_e32 v80, v80
	v_rsq_f32_e32 v76, v76
	v_pk_mul_f32 v[142:143], v[142:143], v[168:169] op_sel_hi:[1,0]
	v_pk_mul_f32 v[144:145], v[144:145], v[168:169] op_sel_hi:[1,0]
	v_pk_mul_f32 v[134:135], v[134:135], v[168:169] op_sel_hi:[1,0]
	v_pk_mul_f32 v[136:137], v[136:137], v[168:169] op_sel_hi:[1,0]
	v_mul_f32_e32 v152, 0xbfb8aa3b, v142
	v_mul_f32_e32 v153, 0xbfb8aa3b, v143
	v_mul_f32_e32 v148, 0xbfb8aa3b, v144
	v_mul_f32_e32 v149, 0xbfb8aa3b, v145
	v_mul_f32_e32 v124, 0xbfb8aa3b, v134
	v_mul_f32_e32 v125, 0xbfb8aa3b, v135
	v_mul_f32_e32 v120, 0xbfb8aa3b, v136
	v_mul_f32_e32 v121, 0xbfb8aa3b, v137
	v_pk_mul_f32 v[138:139], v[138:139], v[168:169] op_sel_hi:[1,0]
	v_pk_mul_f32 v[140:141], v[140:141], v[168:169] op_sel_hi:[1,0]
	v_pk_mul_f32 v[130:131], v[130:131], v[168:169] op_sel_hi:[1,0]
	v_pk_mul_f32 v[132:133], v[132:133], v[168:169] op_sel_hi:[1,0]
	v_exp_f32_e32 v152, v152
	v_exp_f32_e32 v153, v153
	v_exp_f32_e32 v148, v148
	v_exp_f32_e32 v149, v149
	v_exp_f32_e32 v124, v124
	v_exp_f32_e32 v125, v125
	v_exp_f32_e32 v120, v120
	v_exp_f32_e32 v121, v121
	v_mad_i64_i32 v[82:83], vcc, v176, s52, v[170:171]
	v_add_f32_e32 v152, 1.0, v152
	v_add_f32_e32 v153, 1.0, v153
	v_add_f32_e32 v148, 1.0, v148
	v_add_f32_e32 v149, 1.0, v149
	v_add_f32_e32 v124, 1.0, v124
	v_add_f32_e32 v125, 1.0, v125
	v_add_f32_e32 v120, 1.0, v120
	v_add_f32_e32 v121, 1.0, v121
	v_rcp_f32_e32 v152, v152
	v_rcp_f32_e32 v153, v153
	v_rcp_f32_e32 v148, v148
	v_rcp_f32_e32 v149, v149
	v_rcp_f32_e32 v124, v124
	v_rcp_f32_e32 v125, v125
	v_rcp_f32_e32 v120, v120
	v_rcp_f32_e32 v121, v121
	s_nop 0
	v_pk_mul_f32 v[142:143], v[142:143], v[152:153]
	v_pk_mul_f32 v[144:145], v[144:145], v[148:149]
	v_pk_mul_f32 v[134:135], v[134:135], v[124:125]
	v_pk_mul_f32 v[136:137], v[136:137], v[120:121]
	v_pk_mul_f32 v[138:139], v[138:139], v[142:143]
	v_pk_mul_f32 v[140:141], v[140:141], v[144:145]
	v_pk_mul_f32 v[130:131], v[130:131], v[134:135]
	v_pk_mul_f32 v[132:133], v[132:133], v[136:137]
	v_cvt_pk_bf16_f32 v138, v138, v139
	v_cvt_pk_bf16_f32 v139, v140, v141
	v_cvt_pk_bf16_f32 v140, v130, v131
	v_cvt_pk_bf16_f32 v141, v132, v133
	global_store_dwordx4 v[82:83], v[138:141], off
	v_pk_mul_f32 v[126:127], v[126:127], v[208:209] op_sel_hi:[1,0]
	v_pk_mul_f32 v[128:129], v[128:129], v[208:209] op_sel_hi:[1,0]
	v_pk_mul_f32 v[108:109], v[108:109], v[208:209] op_sel_hi:[1,0]
	v_pk_mul_f32 v[110:111], v[110:111], v[208:209] op_sel_hi:[1,0]
	v_mul_f32_e32 v152, 0xbfb8aa3b, v126
	v_mul_f32_e32 v153, 0xbfb8aa3b, v127
	v_mul_f32_e32 v148, 0xbfb8aa3b, v128
	v_mul_f32_e32 v149, 0xbfb8aa3b, v129
	v_mul_f32_e32 v124, 0xbfb8aa3b, v108
	v_mul_f32_e32 v125, 0xbfb8aa3b, v109
	v_mul_f32_e32 v120, 0xbfb8aa3b, v110
	v_mul_f32_e32 v121, 0xbfb8aa3b, v111
	v_pk_mul_f32 v[114:115], v[114:115], v[208:209] op_sel_hi:[1,0]
	v_pk_mul_f32 v[116:117], v[116:117], v[208:209] op_sel_hi:[1,0]
	v_pk_mul_f32 v[104:105], v[104:105], v[208:209] op_sel_hi:[1,0]
	v_pk_mul_f32 v[106:107], v[106:107], v[208:209] op_sel_hi:[1,0]
	v_exp_f32_e32 v152, v152
	v_exp_f32_e32 v153, v153
	v_exp_f32_e32 v148, v148
	v_exp_f32_e32 v149, v149
	v_exp_f32_e32 v124, v124
	v_exp_f32_e32 v125, v125
	v_exp_f32_e32 v120, v120
	v_exp_f32_e32 v121, v121
	v_mad_i64_i32 v[82:83], vcc, v184, s52, v[170:171]
	v_add_f32_e32 v152, 1.0, v152
	v_add_f32_e32 v153, 1.0, v153
	v_add_f32_e32 v148, 1.0, v148
	v_add_f32_e32 v149, 1.0, v149
	v_add_f32_e32 v124, 1.0, v124
	v_add_f32_e32 v125, 1.0, v125
	v_add_f32_e32 v120, 1.0, v120
	v_add_f32_e32 v121, 1.0, v121
	v_rcp_f32_e32 v152, v152
	v_rcp_f32_e32 v153, v153
	v_rcp_f32_e32 v148, v148
	v_rcp_f32_e32 v149, v149
	v_rcp_f32_e32 v124, v124
	v_rcp_f32_e32 v125, v125
	v_rcp_f32_e32 v120, v120
	v_rcp_f32_e32 v121, v121
	s_nop 0
	v_pk_mul_f32 v[126:127], v[126:127], v[152:153]
	v_pk_mul_f32 v[128:129], v[128:129], v[148:149]
	v_pk_mul_f32 v[108:109], v[108:109], v[124:125]
	v_pk_mul_f32 v[110:111], v[110:111], v[120:121]
	v_pk_mul_f32 v[114:115], v[114:115], v[126:127]
	v_pk_mul_f32 v[116:117], v[116:117], v[128:129]
	v_pk_mul_f32 v[104:105], v[104:105], v[108:109]
	v_pk_mul_f32 v[106:107], v[106:107], v[110:111]
	v_cvt_pk_bf16_f32 v114, v114, v115
	v_cvt_pk_bf16_f32 v115, v116, v117
	v_cvt_pk_bf16_f32 v116, v104, v105
	v_cvt_pk_bf16_f32 v117, v106, v107
	global_store_dwordx4 v[82:83], v[114:117], off
	v_pk_mul_f32 v[100:101], v[100:101], v[150:151] op_sel_hi:[1,0]
	v_pk_mul_f32 v[102:103], v[102:103], v[150:151] op_sel_hi:[1,0]
	v_pk_mul_f32 v[92:93], v[92:93], v[150:151] op_sel_hi:[1,0]
	v_pk_mul_f32 v[94:95], v[94:95], v[150:151] op_sel_hi:[1,0]
	v_mul_f32_e32 v152, 0xbfb8aa3b, v100
	v_mul_f32_e32 v153, 0xbfb8aa3b, v101
	v_mul_f32_e32 v148, 0xbfb8aa3b, v102
	v_mul_f32_e32 v149, 0xbfb8aa3b, v103
	v_mul_f32_e32 v124, 0xbfb8aa3b, v92
	v_mul_f32_e32 v125, 0xbfb8aa3b, v93
	v_mul_f32_e32 v120, 0xbfb8aa3b, v94
	v_mul_f32_e32 v121, 0xbfb8aa3b, v95
	v_pk_mul_f32 v[96:97], v[96:97], v[150:151] op_sel_hi:[1,0]
	v_pk_mul_f32 v[98:99], v[98:99], v[150:151] op_sel_hi:[1,0]
	v_pk_mul_f32 v[88:89], v[88:89], v[150:151] op_sel_hi:[1,0]
	v_pk_mul_f32 v[90:91], v[90:91], v[150:151] op_sel_hi:[1,0]
	v_exp_f32_e32 v152, v152
	v_exp_f32_e32 v153, v153
	v_exp_f32_e32 v148, v148
	v_exp_f32_e32 v149, v149
	v_exp_f32_e32 v124, v124
	v_exp_f32_e32 v125, v125
	v_exp_f32_e32 v120, v120
	v_exp_f32_e32 v121, v121
	v_mad_i64_i32 v[82:83], vcc, v182, s52, v[170:171]
	v_add_f32_e32 v152, 1.0, v152
	v_add_f32_e32 v153, 1.0, v153
	v_add_f32_e32 v148, 1.0, v148
	v_add_f32_e32 v149, 1.0, v149
	v_add_f32_e32 v124, 1.0, v124
	v_add_f32_e32 v125, 1.0, v125
	v_add_f32_e32 v120, 1.0, v120
	v_add_f32_e32 v121, 1.0, v121
	v_rcp_f32_e32 v152, v152
	v_rcp_f32_e32 v153, v153
	v_rcp_f32_e32 v148, v148
	v_rcp_f32_e32 v149, v149
	v_rcp_f32_e32 v124, v124
	v_rcp_f32_e32 v125, v125
	v_rcp_f32_e32 v120, v120
	v_rcp_f32_e32 v121, v121
	s_nop 0
	v_pk_mul_f32 v[100:101], v[100:101], v[152:153]
	v_pk_mul_f32 v[102:103], v[102:103], v[148:149]
	v_pk_mul_f32 v[92:93], v[92:93], v[124:125]
	v_pk_mul_f32 v[94:95], v[94:95], v[120:121]
	v_pk_mul_f32 v[96:97], v[96:97], v[100:101]
	v_pk_mul_f32 v[98:99], v[98:99], v[102:103]
	v_pk_mul_f32 v[88:89], v[88:89], v[92:93]
	v_pk_mul_f32 v[90:91], v[90:91], v[94:95]
	v_cvt_pk_bf16_f32 v96, v96, v97
	v_cvt_pk_bf16_f32 v97, v98, v99
	v_cvt_pk_bf16_f32 v98, v88, v89
	v_cvt_pk_bf16_f32 v99, v90, v91
	global_store_dwordx4 v[82:83], v[96:99], off
	v_pk_mul_f32 v[84:85], v[84:85], v[146:147] op_sel_hi:[1,0]
	v_pk_mul_f32 v[86:87], v[86:87], v[146:147] op_sel_hi:[1,0]
	v_pk_mul_f32 v[68:69], v[68:69], v[146:147] op_sel_hi:[1,0]
	v_pk_mul_f32 v[70:71], v[70:71], v[146:147] op_sel_hi:[1,0]
	v_mul_f32_e32 v152, 0xbfb8aa3b, v84
	v_mul_f32_e32 v153, 0xbfb8aa3b, v85
	v_mul_f32_e32 v148, 0xbfb8aa3b, v86
	v_mul_f32_e32 v149, 0xbfb8aa3b, v87
	v_mul_f32_e32 v124, 0xbfb8aa3b, v68
	v_mul_f32_e32 v125, 0xbfb8aa3b, v69
	v_mul_f32_e32 v120, 0xbfb8aa3b, v70
	v_mul_f32_e32 v121, 0xbfb8aa3b, v71
	v_pk_mul_f32 v[72:73], v[72:73], v[146:147] op_sel_hi:[1,0]
	v_pk_mul_f32 v[74:75], v[74:75], v[146:147] op_sel_hi:[1,0]
	v_pk_mul_f32 v[64:65], v[64:65], v[146:147] op_sel_hi:[1,0]
	v_pk_mul_f32 v[66:67], v[66:67], v[146:147] op_sel_hi:[1,0]
	v_exp_f32_e32 v152, v152
	v_exp_f32_e32 v153, v153
	v_exp_f32_e32 v148, v148
	v_exp_f32_e32 v149, v149
	v_exp_f32_e32 v124, v124
	v_exp_f32_e32 v125, v125
	v_exp_f32_e32 v120, v120
	v_exp_f32_e32 v121, v121
	v_mad_i64_i32 v[82:83], vcc, v180, s52, v[170:171]
	v_add_f32_e32 v152, 1.0, v152
	v_add_f32_e32 v153, 1.0, v153
	v_add_f32_e32 v148, 1.0, v148
	v_add_f32_e32 v149, 1.0, v149
	v_add_f32_e32 v124, 1.0, v124
	v_add_f32_e32 v125, 1.0, v125
	v_add_f32_e32 v120, 1.0, v120
	v_add_f32_e32 v121, 1.0, v121
	v_rcp_f32_e32 v152, v152
	v_rcp_f32_e32 v153, v153
	v_rcp_f32_e32 v148, v148
	v_rcp_f32_e32 v149, v149
	v_rcp_f32_e32 v124, v124
	v_rcp_f32_e32 v125, v125
	v_rcp_f32_e32 v120, v120
	v_rcp_f32_e32 v121, v121
	s_nop 0
	v_pk_mul_f32 v[84:85], v[84:85], v[152:153]
	v_pk_mul_f32 v[86:87], v[86:87], v[148:149]
	v_pk_mul_f32 v[68:69], v[68:69], v[124:125]
	v_pk_mul_f32 v[70:71], v[70:71], v[120:121]
	v_pk_mul_f32 v[72:73], v[72:73], v[84:85]
	v_pk_mul_f32 v[74:75], v[74:75], v[86:87]
	v_pk_mul_f32 v[64:65], v[64:65], v[68:69]
	v_pk_mul_f32 v[66:67], v[66:67], v[70:71]
	v_cvt_pk_bf16_f32 v72, v72, v73
	v_cvt_pk_bf16_f32 v73, v74, v75
	v_cvt_pk_bf16_f32 v74, v64, v65
	v_cvt_pk_bf16_f32 v75, v66, v67
	global_store_dwordx4 v[82:83], v[72:75], off
	v_pk_mul_f32 v[60:61], v[60:61], v[122:123] op_sel_hi:[1,0]
	v_pk_mul_f32 v[62:63], v[62:63], v[122:123] op_sel_hi:[1,0]
	v_pk_mul_f32 v[52:53], v[52:53], v[122:123] op_sel_hi:[1,0]
	v_pk_mul_f32 v[54:55], v[54:55], v[122:123] op_sel_hi:[1,0]
	v_mul_f32_e32 v152, 0xbfb8aa3b, v60
	v_mul_f32_e32 v153, 0xbfb8aa3b, v61
	v_mul_f32_e32 v148, 0xbfb8aa3b, v62
	v_mul_f32_e32 v149, 0xbfb8aa3b, v63
	v_mul_f32_e32 v124, 0xbfb8aa3b, v52
	v_mul_f32_e32 v125, 0xbfb8aa3b, v53
	v_mul_f32_e32 v120, 0xbfb8aa3b, v54
	v_mul_f32_e32 v121, 0xbfb8aa3b, v55
	v_pk_mul_f32 v[56:57], v[56:57], v[122:123] op_sel_hi:[1,0]
	v_pk_mul_f32 v[58:59], v[58:59], v[122:123] op_sel_hi:[1,0]
	v_pk_mul_f32 v[48:49], v[48:49], v[122:123] op_sel_hi:[1,0]
	v_pk_mul_f32 v[50:51], v[50:51], v[122:123] op_sel_hi:[1,0]
	v_exp_f32_e32 v152, v152
	v_exp_f32_e32 v153, v153
	v_exp_f32_e32 v148, v148
	v_exp_f32_e32 v149, v149
	v_exp_f32_e32 v124, v124
	v_exp_f32_e32 v125, v125
	v_exp_f32_e32 v120, v120
	v_exp_f32_e32 v121, v121
	v_mad_i64_i32 v[82:83], vcc, v178, s52, v[170:171]
	v_add_f32_e32 v152, 1.0, v152
	v_add_f32_e32 v153, 1.0, v153
	v_add_f32_e32 v148, 1.0, v148
	v_add_f32_e32 v149, 1.0, v149
	v_add_f32_e32 v124, 1.0, v124
	v_add_f32_e32 v125, 1.0, v125
	v_add_f32_e32 v120, 1.0, v120
	v_add_f32_e32 v121, 1.0, v121
	v_rcp_f32_e32 v152, v152
	v_rcp_f32_e32 v153, v153
	v_rcp_f32_e32 v148, v148
	v_rcp_f32_e32 v149, v149
	v_rcp_f32_e32 v124, v124
	v_rcp_f32_e32 v125, v125
	v_rcp_f32_e32 v120, v120
	v_rcp_f32_e32 v121, v121
	s_nop 0
	v_pk_mul_f32 v[60:61], v[60:61], v[152:153]
	v_pk_mul_f32 v[62:63], v[62:63], v[148:149]
	v_pk_mul_f32 v[52:53], v[52:53], v[124:125]
	v_pk_mul_f32 v[54:55], v[54:55], v[120:121]
	v_pk_mul_f32 v[56:57], v[56:57], v[60:61]
	v_pk_mul_f32 v[58:59], v[58:59], v[62:63]
	v_pk_mul_f32 v[48:49], v[48:49], v[52:53]
	v_pk_mul_f32 v[50:51], v[50:51], v[54:55]
	v_cvt_pk_bf16_f32 v56, v56, v57
	v_cvt_pk_bf16_f32 v57, v58, v59
	v_cvt_pk_bf16_f32 v58, v48, v49
	v_cvt_pk_bf16_f32 v59, v50, v51
	global_store_dwordx4 v[82:83], v[56:59], off
	v_pk_mul_f32 v[44:45], v[44:45], v[118:119] op_sel_hi:[1,0]
	v_pk_mul_f32 v[46:47], v[46:47], v[118:119] op_sel_hi:[1,0]
	v_pk_mul_f32 v[36:37], v[36:37], v[118:119] op_sel_hi:[1,0]
	v_pk_mul_f32 v[38:39], v[38:39], v[118:119] op_sel_hi:[1,0]
	v_mul_f32_e32 v152, 0xbfb8aa3b, v44
	v_mul_f32_e32 v153, 0xbfb8aa3b, v45
	v_mul_f32_e32 v148, 0xbfb8aa3b, v46
	v_mul_f32_e32 v149, 0xbfb8aa3b, v47
	v_mul_f32_e32 v124, 0xbfb8aa3b, v36
	v_mul_f32_e32 v125, 0xbfb8aa3b, v37
	v_mul_f32_e32 v120, 0xbfb8aa3b, v38
	v_mul_f32_e32 v121, 0xbfb8aa3b, v39
	v_pk_mul_f32 v[40:41], v[40:41], v[118:119] op_sel_hi:[1,0]
	v_pk_mul_f32 v[42:43], v[42:43], v[118:119] op_sel_hi:[1,0]
	v_pk_mul_f32 v[32:33], v[32:33], v[118:119] op_sel_hi:[1,0]
	v_pk_mul_f32 v[34:35], v[34:35], v[118:119] op_sel_hi:[1,0]
	v_exp_f32_e32 v152, v152
	v_exp_f32_e32 v153, v153
	v_exp_f32_e32 v148, v148
	v_exp_f32_e32 v149, v149
	v_exp_f32_e32 v124, v124
	v_exp_f32_e32 v125, v125
	v_exp_f32_e32 v120, v120
	v_exp_f32_e32 v121, v121
	v_mad_i64_i32 v[82:83], vcc, v174, s52, v[170:171]
	v_add_f32_e32 v152, 1.0, v152
	v_add_f32_e32 v153, 1.0, v153
	v_add_f32_e32 v148, 1.0, v148
	v_add_f32_e32 v149, 1.0, v149
	v_add_f32_e32 v124, 1.0, v124
	v_add_f32_e32 v125, 1.0, v125
	v_add_f32_e32 v120, 1.0, v120
	v_add_f32_e32 v121, 1.0, v121
	v_rcp_f32_e32 v152, v152
	v_rcp_f32_e32 v153, v153
	v_rcp_f32_e32 v148, v148
	v_rcp_f32_e32 v149, v149
	v_rcp_f32_e32 v124, v124
	v_rcp_f32_e32 v125, v125
	v_rcp_f32_e32 v120, v120
	v_rcp_f32_e32 v121, v121
	s_nop 0
	v_pk_mul_f32 v[44:45], v[44:45], v[152:153]
	v_pk_mul_f32 v[46:47], v[46:47], v[148:149]
	v_pk_mul_f32 v[36:37], v[36:37], v[124:125]
	v_pk_mul_f32 v[38:39], v[38:39], v[120:121]
	v_pk_mul_f32 v[40:41], v[40:41], v[44:45]
	v_pk_mul_f32 v[42:43], v[42:43], v[46:47]
	v_pk_mul_f32 v[32:33], v[32:33], v[36:37]
	v_pk_mul_f32 v[34:35], v[34:35], v[38:39]
	v_cvt_pk_bf16_f32 v40, v40, v41
	v_cvt_pk_bf16_f32 v41, v42, v43
	v_cvt_pk_bf16_f32 v42, v32, v33
	v_cvt_pk_bf16_f32 v43, v34, v35
	global_store_dwordx4 v[82:83], v[40:43], off
	v_pk_mul_f32 v[28:29], v[28:29], v[80:81] op_sel_hi:[1,0]
	v_pk_mul_f32 v[30:31], v[30:31], v[80:81] op_sel_hi:[1,0]
	v_pk_mul_f32 v[20:21], v[20:21], v[80:81] op_sel_hi:[1,0]
	v_pk_mul_f32 v[22:23], v[22:23], v[80:81] op_sel_hi:[1,0]
	v_mul_f32_e32 v152, 0xbfb8aa3b, v28
	v_mul_f32_e32 v153, 0xbfb8aa3b, v29
	v_mul_f32_e32 v148, 0xbfb8aa3b, v30
	v_mul_f32_e32 v149, 0xbfb8aa3b, v31
	v_mul_f32_e32 v124, 0xbfb8aa3b, v20
	v_mul_f32_e32 v125, 0xbfb8aa3b, v21
	v_mul_f32_e32 v120, 0xbfb8aa3b, v22
	v_mul_f32_e32 v121, 0xbfb8aa3b, v23
	v_pk_mul_f32 v[24:25], v[24:25], v[80:81] op_sel_hi:[1,0]
	v_pk_mul_f32 v[26:27], v[26:27], v[80:81] op_sel_hi:[1,0]
	v_pk_mul_f32 v[16:17], v[16:17], v[80:81] op_sel_hi:[1,0]
	v_pk_mul_f32 v[18:19], v[18:19], v[80:81] op_sel_hi:[1,0]
	v_exp_f32_e32 v152, v152
	v_exp_f32_e32 v153, v153
	v_exp_f32_e32 v148, v148
	v_exp_f32_e32 v149, v149
	v_exp_f32_e32 v124, v124
	v_exp_f32_e32 v125, v125
	v_exp_f32_e32 v120, v120
	v_exp_f32_e32 v121, v121
	v_mad_i64_i32 v[82:83], vcc, v172, s52, v[170:171]
	v_add_f32_e32 v152, 1.0, v152
	v_add_f32_e32 v153, 1.0, v153
	v_add_f32_e32 v148, 1.0, v148
	v_add_f32_e32 v149, 1.0, v149
	v_add_f32_e32 v124, 1.0, v124
	v_add_f32_e32 v125, 1.0, v125
	v_add_f32_e32 v120, 1.0, v120
	v_add_f32_e32 v121, 1.0, v121
	v_rcp_f32_e32 v152, v152
	v_rcp_f32_e32 v153, v153
	v_rcp_f32_e32 v148, v148
	v_rcp_f32_e32 v149, v149
	v_rcp_f32_e32 v124, v124
	v_rcp_f32_e32 v125, v125
	v_rcp_f32_e32 v120, v120
	v_rcp_f32_e32 v121, v121
	s_nop 0
	v_pk_mul_f32 v[28:29], v[28:29], v[152:153]
	v_pk_mul_f32 v[30:31], v[30:31], v[148:149]
	v_pk_mul_f32 v[20:21], v[20:21], v[124:125]
	v_pk_mul_f32 v[22:23], v[22:23], v[120:121]
	v_pk_mul_f32 v[24:25], v[24:25], v[28:29]
	v_pk_mul_f32 v[26:27], v[26:27], v[30:31]
	v_pk_mul_f32 v[16:17], v[16:17], v[20:21]
	v_pk_mul_f32 v[18:19], v[18:19], v[22:23]
	v_cvt_pk_bf16_f32 v24, v24, v25
	v_cvt_pk_bf16_f32 v25, v26, v27
	v_cvt_pk_bf16_f32 v26, v16, v17
	v_cvt_pk_bf16_f32 v27, v18, v19
	global_store_dwordx4 v[82:83], v[24:27], off
	v_pk_mul_f32 v[12:13], v[12:13], v[76:77] op_sel_hi:[1,0]
	v_pk_mul_f32 v[14:15], v[14:15], v[76:77] op_sel_hi:[1,0]
	v_pk_mul_f32 v[4:5], v[4:5], v[76:77] op_sel_hi:[1,0]
	v_pk_mul_f32 v[6:7], v[6:7], v[76:77] op_sel_hi:[1,0]
	v_mul_f32_e32 v152, 0xbfb8aa3b, v12
	v_mul_f32_e32 v153, 0xbfb8aa3b, v13
	v_mul_f32_e32 v148, 0xbfb8aa3b, v14
	v_mul_f32_e32 v149, 0xbfb8aa3b, v15
	v_mul_f32_e32 v124, 0xbfb8aa3b, v4
	v_mul_f32_e32 v125, 0xbfb8aa3b, v5
	v_mul_f32_e32 v120, 0xbfb8aa3b, v6
	v_mul_f32_e32 v121, 0xbfb8aa3b, v7
	v_pk_mul_f32 v[8:9], v[8:9], v[76:77] op_sel_hi:[1,0]
	v_pk_mul_f32 v[10:11], v[10:11], v[76:77] op_sel_hi:[1,0]
	v_pk_mul_f32 v[0:1], v[0:1], v[76:77] op_sel_hi:[1,0]
	v_pk_mul_f32 v[2:3], v[2:3], v[76:77] op_sel_hi:[1,0]
	v_exp_f32_e32 v152, v152
	v_exp_f32_e32 v153, v153
	v_exp_f32_e32 v148, v148
	v_exp_f32_e32 v149, v149
	v_exp_f32_e32 v124, v124
	v_exp_f32_e32 v125, v125
	v_exp_f32_e32 v120, v120
	v_exp_f32_e32 v121, v121
	v_mad_i64_i32 v[82:83], vcc, v166, s52, v[170:171]
	v_add_f32_e32 v152, 1.0, v152
	v_add_f32_e32 v153, 1.0, v153
	v_add_f32_e32 v148, 1.0, v148
	v_add_f32_e32 v149, 1.0, v149
	v_add_f32_e32 v124, 1.0, v124
	v_add_f32_e32 v125, 1.0, v125
	v_add_f32_e32 v120, 1.0, v120
	v_add_f32_e32 v121, 1.0, v121
	v_rcp_f32_e32 v152, v152
	v_rcp_f32_e32 v153, v153
	v_rcp_f32_e32 v148, v148
	v_rcp_f32_e32 v149, v149
	v_rcp_f32_e32 v124, v124
	v_rcp_f32_e32 v125, v125
	v_rcp_f32_e32 v120, v120
	v_rcp_f32_e32 v121, v121
	s_nop 0
	v_pk_mul_f32 v[12:13], v[12:13], v[152:153]
	v_pk_mul_f32 v[14:15], v[14:15], v[148:149]
	v_pk_mul_f32 v[4:5], v[4:5], v[124:125]
	v_pk_mul_f32 v[6:7], v[6:7], v[120:121]
	v_pk_mul_f32 v[8:9], v[8:9], v[12:13]
	v_pk_mul_f32 v[10:11], v[10:11], v[14:15]
	v_pk_mul_f32 v[0:1], v[0:1], v[4:5]
	v_pk_mul_f32 v[2:3], v[2:3], v[6:7]
	v_cvt_pk_bf16_f32 v8, v8, v9
	v_cvt_pk_bf16_f32 v9, v10, v11
	v_cvt_pk_bf16_f32 v10, v0, v1
	v_cvt_pk_bf16_f32 v11, v2, v3
	global_store_dwordx4 v[82:83], v[8:11], off
	s_andn2_b64 vcc, exec, s[4:5]
	s_mov_b64 s[6:7], -1
	s_cbranch_vccnz .LBB0_272
	s_waitcnt vmcnt(0)
	s_andn2_b64 vcc, exec, s[8:9]
	s_cbranch_vccnz .LBB0_271
	s_barrier
	s_branch .LBB0_271

.LBB0_1474:
	v_lshl_add_u32 v176, s6, 8, v203
	v_ashrrev_i32_e32 v177, 31, v176
	v_lshlrev_b64 v[76:77], 6, v[176:177]
	v_lshl_add_u64 v[76:77], v[160:161], 0, v[76:77]
	v_or_b32_e32 v184, 16, v176
	global_load_dwordx4 v[168:171], v[76:77], off
	v_ashrrev_i32_e32 v185, 31, v184
	v_lshlrev_b64 v[76:77], 6, v[184:185]
	v_lshl_add_u64 v[76:77], v[160:161], 0, v[76:77]
	global_load_dwordx4 v[194:197], v[76:77], off
	v_or_b32_e32 v182, 32, v176
	v_ashrrev_i32_e32 v183, 31, v182
	v_lshlrev_b64 v[76:77], 6, v[182:183]
	v_or_b32_e32 v180, 48, v176
	v_lshl_add_u64 v[76:77], v[160:161], 0, v[76:77]
	v_ashrrev_i32_e32 v181, 31, v180
	global_load_dwordx4 v[150:153], v[76:77], off
	v_lshlrev_b64 v[76:77], 6, v[180:181]
	v_add_u32_e32 v178, 0x80, v176
	v_lshl_add_u64 v[76:77], v[160:161], 0, v[76:77]
	v_ashrrev_i32_e32 v179, 31, v178
	global_load_dwordx4 v[146:149], v[76:77], off
	v_lshlrev_b64 v[76:77], 6, v[178:179]
	v_add_u32_e32 v174, 0x90, v176
	v_lshl_add_u64 v[76:77], v[160:161], 0, v[76:77]
	v_ashrrev_i32_e32 v175, 31, v174
	global_load_dwordx4 v[122:125], v[76:77], off
	v_lshlrev_b64 v[76:77], 6, v[174:175]
	v_add_u32_e32 v172, 0xa0, v176
	v_lshl_add_u64 v[76:77], v[160:161], 0, v[76:77]
	v_ashrrev_i32_e32 v173, 31, v172
	v_lshl_or_b32 v198, s7, 7, v205
	global_load_dwordx4 v[118:121], v[76:77], off
	v_lshlrev_b64 v[76:77], 6, v[172:173]
	v_add_u32_e32 v166, 0xb0, v176
	v_ashrrev_i32_e32 v199, 31, v198
	v_lshl_add_u64 v[76:77], v[160:161], 0, v[76:77]
	v_ashrrev_i32_e32 v167, 31, v166
	v_and_b32_e32 v173, 64, v245
	global_load_dwordx4 v[80:83], v[76:77], off
	v_lshlrev_b64 v[76:77], 6, v[166:167]
	v_xor_b32_e32 v167, 16, v245
	v_add_u32_e32 v175, 64, v173
	v_cmp_lt_i32_e32 vcc, v167, v175
	s_mov_b32 s22, 0x3a800000
	v_lshl_add_u64 v[76:77], v[160:161], 0, v[76:77]
	v_cndmask_b32_e32 v167, v245, v167, vcc
	v_lshlrev_b32_e32 v173, 2, v167
	v_xor_b32_e32 v167, 32, v245
	v_cmp_lt_i32_e32 vcc, v167, v175
	global_load_dwordx4 v[76:79], v[76:77], off
	v_readlane_b32 s50, v255, 34
	v_cndmask_b32_e32 v167, v245, v167, vcc
	v_lshlrev_b32_e32 v167, 2, v167
	v_readlane_b32 s51, v255, 35
	s_waitcnt vmcnt(0)
	v_add_f32_e32 v169, v169, v168
	v_add_f32_e32 v171, v170, v171
	v_add_f32_e32 v195, v195, v194
	v_add_f32_e32 v197, v196, v197
	v_add_f32_e32 v151, v151, v150
	v_add_f32_e32 v153, v152, v153
	v_add_f32_e32 v147, v147, v146
	v_add_f32_e32 v149, v148, v149
	v_add_f32_e32 v123, v123, v122
	v_add_f32_e32 v125, v124, v125
	v_add_f32_e32 v119, v119, v118
	v_add_f32_e32 v121, v120, v121
	v_add_f32_e32 v81, v81, v80
	v_add_f32_e32 v83, v82, v83
	v_add_f32_e32 v77, v77, v76
	v_add_f32_e32 v79, v78, v79
	v_add_f32_e32 v168, v169, v171
	v_add_f32_e32 v194, v195, v197
	v_add_f32_e32 v150, v151, v153
	v_add_f32_e32 v146, v147, v149
	v_add_f32_e32 v122, v123, v125
	v_add_f32_e32 v118, v119, v121
	v_add_f32_e32 v80, v81, v83
	v_add_f32_e32 v76, v77, v79
	ds_bpermute_b32 v169, v173, v168
	ds_bpermute_b32 v195, v173, v194
	ds_bpermute_b32 v151, v173, v150
	ds_bpermute_b32 v147, v173, v146
	ds_bpermute_b32 v123, v173, v122
	ds_bpermute_b32 v119, v173, v118
	ds_bpermute_b32 v81, v173, v80
	ds_bpermute_b32 v77, v173, v76
	v_lshlrev_b64 v[170:171], 1, v[198:199]
	v_lshl_add_u64 v[170:171], s[10:11], 0, v[170:171]
	s_waitcnt lgkmcnt(0)
	v_add_f32_e32 v168, v168, v169
	v_add_f32_e32 v194, v194, v195
	v_add_f32_e32 v150, v150, v151
	v_add_f32_e32 v146, v146, v147
	v_add_f32_e32 v122, v122, v123
	v_add_f32_e32 v118, v118, v119
	v_add_f32_e32 v80, v80, v81
	v_add_f32_e32 v76, v76, v77
	ds_bpermute_b32 v169, v167, v168
	ds_bpermute_b32 v195, v167, v194
	ds_bpermute_b32 v151, v167, v150
	ds_bpermute_b32 v147, v167, v146
	ds_bpermute_b32 v123, v167, v122
	ds_bpermute_b32 v119, v167, v118
	ds_bpermute_b32 v81, v167, v80
	ds_bpermute_b32 v77, v167, v76
	s_waitcnt lgkmcnt(0)
	v_add_f32_e32 v168, v168, v169
	v_add_f32_e32 v194, v194, v195
	v_add_f32_e32 v150, v150, v151
	v_add_f32_e32 v146, v146, v147
	v_add_f32_e32 v122, v122, v123
	v_add_f32_e32 v118, v118, v119
	v_add_f32_e32 v80, v80, v81
	v_add_f32_e32 v76, v76, v77
	v_mov_b32_e32 v78, 0x358637bd
	v_fma_f32 v168, v168, s22, v78
	v_fma_f32 v194, v194, s22, v78
	v_fma_f32 v150, v150, s22, v78
	v_fma_f32 v146, v146, s22, v78
	v_fma_f32 v122, v122, s22, v78
	v_fma_f32 v118, v118, s22, v78
	v_fma_f32 v80, v80, s22, v78
	v_fma_f32 v76, v76, s22, v78
	v_rsq_f32_e32 v168, v168
	v_rsq_f32_e32 v194, v194
	v_rsq_f32_e32 v150, v150
	v_rsq_f32_e32 v146, v146
	v_rsq_f32_e32 v122, v122
	v_rsq_f32_e32 v118, v118
	v_rsq_f32_e32 v80, v80
	v_rsq_f32_e32 v76, v76
	v_pk_mul_f32 v[142:143], v[142:143], v[168:169] op_sel_hi:[1,0]
	v_pk_mul_f32 v[144:145], v[144:145], v[168:169] op_sel_hi:[1,0]
	v_pk_mul_f32 v[134:135], v[134:135], v[168:169] op_sel_hi:[1,0]
	v_pk_mul_f32 v[136:137], v[136:137], v[168:169] op_sel_hi:[1,0]
	v_mul_f32_e32 v152, 0xbfb8aa3b, v142
	v_mul_f32_e32 v153, 0xbfb8aa3b, v143
	v_mul_f32_e32 v148, 0xbfb8aa3b, v144
	v_mul_f32_e32 v149, 0xbfb8aa3b, v145
	v_mul_f32_e32 v124, 0xbfb8aa3b, v134
	v_mul_f32_e32 v125, 0xbfb8aa3b, v135
	v_mul_f32_e32 v120, 0xbfb8aa3b, v136
	v_mul_f32_e32 v121, 0xbfb8aa3b, v137
	v_pk_mul_f32 v[138:139], v[138:139], v[168:169] op_sel_hi:[1,0]
	v_pk_mul_f32 v[140:141], v[140:141], v[168:169] op_sel_hi:[1,0]
	v_pk_mul_f32 v[130:131], v[130:131], v[168:169] op_sel_hi:[1,0]
	v_pk_mul_f32 v[132:133], v[132:133], v[168:169] op_sel_hi:[1,0]
	v_exp_f32_e32 v152, v152
	v_exp_f32_e32 v153, v153
	v_exp_f32_e32 v148, v148
	v_exp_f32_e32 v149, v149
	v_exp_f32_e32 v124, v124
	v_exp_f32_e32 v125, v125
	v_exp_f32_e32 v120, v120
	v_exp_f32_e32 v121, v121
	v_mad_i64_i32 v[82:83], vcc, v176, s52, v[170:171]
	v_add_f32_e32 v152, 1.0, v152
	v_add_f32_e32 v153, 1.0, v153
	v_add_f32_e32 v148, 1.0, v148
	v_add_f32_e32 v149, 1.0, v149
	v_add_f32_e32 v124, 1.0, v124
	v_add_f32_e32 v125, 1.0, v125
	v_add_f32_e32 v120, 1.0, v120
	v_add_f32_e32 v121, 1.0, v121
	v_rcp_f32_e32 v152, v152
	v_rcp_f32_e32 v153, v153
	v_rcp_f32_e32 v148, v148
	v_rcp_f32_e32 v149, v149
	v_rcp_f32_e32 v124, v124
	v_rcp_f32_e32 v125, v125
	v_rcp_f32_e32 v120, v120
	v_rcp_f32_e32 v121, v121
	s_nop 0
	v_pk_mul_f32 v[142:143], v[142:143], v[152:153]
	v_pk_mul_f32 v[144:145], v[144:145], v[148:149]
	v_pk_mul_f32 v[134:135], v[134:135], v[124:125]
	v_pk_mul_f32 v[136:137], v[136:137], v[120:121]
	v_pk_mul_f32 v[138:139], v[138:139], v[142:143]
	v_pk_mul_f32 v[140:141], v[140:141], v[144:145]
	v_pk_mul_f32 v[130:131], v[130:131], v[134:135]
	v_pk_mul_f32 v[132:133], v[132:133], v[136:137]
	v_cvt_pk_bf16_f32 v138, v138, v139
	v_cvt_pk_bf16_f32 v139, v140, v141
	v_cvt_pk_bf16_f32 v140, v130, v131
	v_cvt_pk_bf16_f32 v141, v132, v133
	global_store_dwordx4 v[82:83], v[138:141], off
	v_pk_mul_f32 v[126:127], v[126:127], v[194:195] op_sel_hi:[1,0]
	v_pk_mul_f32 v[128:129], v[128:129], v[194:195] op_sel_hi:[1,0]
	v_pk_mul_f32 v[108:109], v[108:109], v[194:195] op_sel_hi:[1,0]
	v_pk_mul_f32 v[110:111], v[110:111], v[194:195] op_sel_hi:[1,0]
	v_mul_f32_e32 v152, 0xbfb8aa3b, v126
	v_mul_f32_e32 v153, 0xbfb8aa3b, v127
	v_mul_f32_e32 v148, 0xbfb8aa3b, v128
	v_mul_f32_e32 v149, 0xbfb8aa3b, v129
	v_mul_f32_e32 v124, 0xbfb8aa3b, v108
	v_mul_f32_e32 v125, 0xbfb8aa3b, v109
	v_mul_f32_e32 v120, 0xbfb8aa3b, v110
	v_mul_f32_e32 v121, 0xbfb8aa3b, v111
	v_pk_mul_f32 v[114:115], v[114:115], v[194:195] op_sel_hi:[1,0]
	v_pk_mul_f32 v[116:117], v[116:117], v[194:195] op_sel_hi:[1,0]
	v_pk_mul_f32 v[104:105], v[104:105], v[194:195] op_sel_hi:[1,0]
	v_pk_mul_f32 v[106:107], v[106:107], v[194:195] op_sel_hi:[1,0]
	v_exp_f32_e32 v152, v152
	v_exp_f32_e32 v153, v153
	v_exp_f32_e32 v148, v148
	v_exp_f32_e32 v149, v149
	v_exp_f32_e32 v124, v124
	v_exp_f32_e32 v125, v125
	v_exp_f32_e32 v120, v120
	v_exp_f32_e32 v121, v121
	v_mad_i64_i32 v[82:83], vcc, v184, s52, v[170:171]
	v_add_f32_e32 v152, 1.0, v152
	v_add_f32_e32 v153, 1.0, v153
	v_add_f32_e32 v148, 1.0, v148
	v_add_f32_e32 v149, 1.0, v149
	v_add_f32_e32 v124, 1.0, v124
	v_add_f32_e32 v125, 1.0, v125
	v_add_f32_e32 v120, 1.0, v120
	v_add_f32_e32 v121, 1.0, v121
	v_rcp_f32_e32 v152, v152
	v_rcp_f32_e32 v153, v153
	v_rcp_f32_e32 v148, v148
	v_rcp_f32_e32 v149, v149
	v_rcp_f32_e32 v124, v124
	v_rcp_f32_e32 v125, v125
	v_rcp_f32_e32 v120, v120
	v_rcp_f32_e32 v121, v121
	s_nop 0
	v_pk_mul_f32 v[126:127], v[126:127], v[152:153]
	v_pk_mul_f32 v[128:129], v[128:129], v[148:149]
	v_pk_mul_f32 v[108:109], v[108:109], v[124:125]
	v_pk_mul_f32 v[110:111], v[110:111], v[120:121]
	v_pk_mul_f32 v[114:115], v[114:115], v[126:127]
	v_pk_mul_f32 v[116:117], v[116:117], v[128:129]
	v_pk_mul_f32 v[104:105], v[104:105], v[108:109]
	v_pk_mul_f32 v[106:107], v[106:107], v[110:111]
	v_cvt_pk_bf16_f32 v114, v114, v115
	v_cvt_pk_bf16_f32 v115, v116, v117
	v_cvt_pk_bf16_f32 v116, v104, v105
	v_cvt_pk_bf16_f32 v117, v106, v107
	global_store_dwordx4 v[82:83], v[114:117], off
	v_pk_mul_f32 v[100:101], v[100:101], v[150:151] op_sel_hi:[1,0]
	v_pk_mul_f32 v[102:103], v[102:103], v[150:151] op_sel_hi:[1,0]
	v_pk_mul_f32 v[92:93], v[92:93], v[150:151] op_sel_hi:[1,0]
	v_pk_mul_f32 v[94:95], v[94:95], v[150:151] op_sel_hi:[1,0]
	v_mul_f32_e32 v152, 0xbfb8aa3b, v100
	v_mul_f32_e32 v153, 0xbfb8aa3b, v101
	v_mul_f32_e32 v148, 0xbfb8aa3b, v102
	v_mul_f32_e32 v149, 0xbfb8aa3b, v103
	v_mul_f32_e32 v124, 0xbfb8aa3b, v92
	v_mul_f32_e32 v125, 0xbfb8aa3b, v93
	v_mul_f32_e32 v120, 0xbfb8aa3b, v94
	v_mul_f32_e32 v121, 0xbfb8aa3b, v95
	v_pk_mul_f32 v[96:97], v[96:97], v[150:151] op_sel_hi:[1,0]
	v_pk_mul_f32 v[98:99], v[98:99], v[150:151] op_sel_hi:[1,0]
	v_pk_mul_f32 v[88:89], v[88:89], v[150:151] op_sel_hi:[1,0]
	v_pk_mul_f32 v[90:91], v[90:91], v[150:151] op_sel_hi:[1,0]
	v_exp_f32_e32 v152, v152
	v_exp_f32_e32 v153, v153
	v_exp_f32_e32 v148, v148
	v_exp_f32_e32 v149, v149
	v_exp_f32_e32 v124, v124
	v_exp_f32_e32 v125, v125
	v_exp_f32_e32 v120, v120
	v_exp_f32_e32 v121, v121
	v_mad_i64_i32 v[82:83], vcc, v182, s52, v[170:171]
	v_add_f32_e32 v152, 1.0, v152
	v_add_f32_e32 v153, 1.0, v153
	v_add_f32_e32 v148, 1.0, v148
	v_add_f32_e32 v149, 1.0, v149
	v_add_f32_e32 v124, 1.0, v124
	v_add_f32_e32 v125, 1.0, v125
	v_add_f32_e32 v120, 1.0, v120
	v_add_f32_e32 v121, 1.0, v121
	v_rcp_f32_e32 v152, v152
	v_rcp_f32_e32 v153, v153
	v_rcp_f32_e32 v148, v148
	v_rcp_f32_e32 v149, v149
	v_rcp_f32_e32 v124, v124
	v_rcp_f32_e32 v125, v125
	v_rcp_f32_e32 v120, v120
	v_rcp_f32_e32 v121, v121
	s_nop 0
	v_pk_mul_f32 v[100:101], v[100:101], v[152:153]
	v_pk_mul_f32 v[102:103], v[102:103], v[148:149]
	v_pk_mul_f32 v[92:93], v[92:93], v[124:125]
	v_pk_mul_f32 v[94:95], v[94:95], v[120:121]
	v_pk_mul_f32 v[96:97], v[96:97], v[100:101]
	v_pk_mul_f32 v[98:99], v[98:99], v[102:103]
	v_pk_mul_f32 v[88:89], v[88:89], v[92:93]
	v_pk_mul_f32 v[90:91], v[90:91], v[94:95]
	v_cvt_pk_bf16_f32 v96, v96, v97
	v_cvt_pk_bf16_f32 v97, v98, v99
	v_cvt_pk_bf16_f32 v98, v88, v89
	v_cvt_pk_bf16_f32 v99, v90, v91
	global_store_dwordx4 v[82:83], v[96:99], off
	v_pk_mul_f32 v[84:85], v[84:85], v[146:147] op_sel_hi:[1,0]
	v_pk_mul_f32 v[86:87], v[86:87], v[146:147] op_sel_hi:[1,0]
	v_pk_mul_f32 v[68:69], v[68:69], v[146:147] op_sel_hi:[1,0]
	v_pk_mul_f32 v[70:71], v[70:71], v[146:147] op_sel_hi:[1,0]
	v_mul_f32_e32 v152, 0xbfb8aa3b, v84
	v_mul_f32_e32 v153, 0xbfb8aa3b, v85
	v_mul_f32_e32 v148, 0xbfb8aa3b, v86
	v_mul_f32_e32 v149, 0xbfb8aa3b, v87
	v_mul_f32_e32 v124, 0xbfb8aa3b, v68
	v_mul_f32_e32 v125, 0xbfb8aa3b, v69
	v_mul_f32_e32 v120, 0xbfb8aa3b, v70
	v_mul_f32_e32 v121, 0xbfb8aa3b, v71
	v_pk_mul_f32 v[72:73], v[72:73], v[146:147] op_sel_hi:[1,0]
	v_pk_mul_f32 v[74:75], v[74:75], v[146:147] op_sel_hi:[1,0]
	v_pk_mul_f32 v[64:65], v[64:65], v[146:147] op_sel_hi:[1,0]
	v_pk_mul_f32 v[66:67], v[66:67], v[146:147] op_sel_hi:[1,0]
	v_exp_f32_e32 v152, v152
	v_exp_f32_e32 v153, v153
	v_exp_f32_e32 v148, v148
	v_exp_f32_e32 v149, v149
	v_exp_f32_e32 v124, v124
	v_exp_f32_e32 v125, v125
	v_exp_f32_e32 v120, v120
	v_exp_f32_e32 v121, v121
	v_mad_i64_i32 v[82:83], vcc, v180, s52, v[170:171]
	v_add_f32_e32 v152, 1.0, v152
	v_add_f32_e32 v153, 1.0, v153
	v_add_f32_e32 v148, 1.0, v148
	v_add_f32_e32 v149, 1.0, v149
	v_add_f32_e32 v124, 1.0, v124
	v_add_f32_e32 v125, 1.0, v125
	v_add_f32_e32 v120, 1.0, v120
	v_add_f32_e32 v121, 1.0, v121
	v_rcp_f32_e32 v152, v152
	v_rcp_f32_e32 v153, v153
	v_rcp_f32_e32 v148, v148
	v_rcp_f32_e32 v149, v149
	v_rcp_f32_e32 v124, v124
	v_rcp_f32_e32 v125, v125
	v_rcp_f32_e32 v120, v120
	v_rcp_f32_e32 v121, v121
	s_nop 0
	v_pk_mul_f32 v[84:85], v[84:85], v[152:153]
	v_pk_mul_f32 v[86:87], v[86:87], v[148:149]
	v_pk_mul_f32 v[68:69], v[68:69], v[124:125]
	v_pk_mul_f32 v[70:71], v[70:71], v[120:121]
	v_pk_mul_f32 v[72:73], v[72:73], v[84:85]
	v_pk_mul_f32 v[74:75], v[74:75], v[86:87]
	v_pk_mul_f32 v[64:65], v[64:65], v[68:69]
	v_pk_mul_f32 v[66:67], v[66:67], v[70:71]
	v_cvt_pk_bf16_f32 v72, v72, v73
	v_cvt_pk_bf16_f32 v73, v74, v75
	v_cvt_pk_bf16_f32 v74, v64, v65
	v_cvt_pk_bf16_f32 v75, v66, v67
	global_store_dwordx4 v[82:83], v[72:75], off
	v_pk_mul_f32 v[60:61], v[60:61], v[122:123] op_sel_hi:[1,0]
	v_pk_mul_f32 v[62:63], v[62:63], v[122:123] op_sel_hi:[1,0]
	v_pk_mul_f32 v[52:53], v[52:53], v[122:123] op_sel_hi:[1,0]
	v_pk_mul_f32 v[54:55], v[54:55], v[122:123] op_sel_hi:[1,0]
	v_mul_f32_e32 v152, 0xbfb8aa3b, v60
	v_mul_f32_e32 v153, 0xbfb8aa3b, v61
	v_mul_f32_e32 v148, 0xbfb8aa3b, v62
	v_mul_f32_e32 v149, 0xbfb8aa3b, v63
	v_mul_f32_e32 v124, 0xbfb8aa3b, v52
	v_mul_f32_e32 v125, 0xbfb8aa3b, v53
	v_mul_f32_e32 v120, 0xbfb8aa3b, v54
	v_mul_f32_e32 v121, 0xbfb8aa3b, v55
	v_pk_mul_f32 v[56:57], v[56:57], v[122:123] op_sel_hi:[1,0]
	v_pk_mul_f32 v[58:59], v[58:59], v[122:123] op_sel_hi:[1,0]
	v_pk_mul_f32 v[48:49], v[48:49], v[122:123] op_sel_hi:[1,0]
	v_pk_mul_f32 v[50:51], v[50:51], v[122:123] op_sel_hi:[1,0]
	v_exp_f32_e32 v152, v152
	v_exp_f32_e32 v153, v153
	v_exp_f32_e32 v148, v148
	v_exp_f32_e32 v149, v149
	v_exp_f32_e32 v124, v124
	v_exp_f32_e32 v125, v125
	v_exp_f32_e32 v120, v120
	v_exp_f32_e32 v121, v121
	v_mad_i64_i32 v[82:83], vcc, v178, s52, v[170:171]
	v_add_f32_e32 v152, 1.0, v152
	v_add_f32_e32 v153, 1.0, v153
	v_add_f32_e32 v148, 1.0, v148
	v_add_f32_e32 v149, 1.0, v149
	v_add_f32_e32 v124, 1.0, v124
	v_add_f32_e32 v125, 1.0, v125
	v_add_f32_e32 v120, 1.0, v120
	v_add_f32_e32 v121, 1.0, v121
	v_rcp_f32_e32 v152, v152
	v_rcp_f32_e32 v153, v153
	v_rcp_f32_e32 v148, v148
	v_rcp_f32_e32 v149, v149
	v_rcp_f32_e32 v124, v124
	v_rcp_f32_e32 v125, v125
	v_rcp_f32_e32 v120, v120
	v_rcp_f32_e32 v121, v121
	s_nop 0
	v_pk_mul_f32 v[60:61], v[60:61], v[152:153]
	v_pk_mul_f32 v[62:63], v[62:63], v[148:149]
	v_pk_mul_f32 v[52:53], v[52:53], v[124:125]
	v_pk_mul_f32 v[54:55], v[54:55], v[120:121]
	v_pk_mul_f32 v[56:57], v[56:57], v[60:61]
	v_pk_mul_f32 v[58:59], v[58:59], v[62:63]
	v_pk_mul_f32 v[48:49], v[48:49], v[52:53]
	v_pk_mul_f32 v[50:51], v[50:51], v[54:55]
	v_cvt_pk_bf16_f32 v56, v56, v57
	v_cvt_pk_bf16_f32 v57, v58, v59
	v_cvt_pk_bf16_f32 v58, v48, v49
	v_cvt_pk_bf16_f32 v59, v50, v51
	global_store_dwordx4 v[82:83], v[56:59], off
	v_pk_mul_f32 v[44:45], v[44:45], v[118:119] op_sel_hi:[1,0]
	v_pk_mul_f32 v[46:47], v[46:47], v[118:119] op_sel_hi:[1,0]
	v_pk_mul_f32 v[36:37], v[36:37], v[118:119] op_sel_hi:[1,0]
	v_pk_mul_f32 v[38:39], v[38:39], v[118:119] op_sel_hi:[1,0]
	v_mul_f32_e32 v152, 0xbfb8aa3b, v44
	v_mul_f32_e32 v153, 0xbfb8aa3b, v45
	v_mul_f32_e32 v148, 0xbfb8aa3b, v46
	v_mul_f32_e32 v149, 0xbfb8aa3b, v47
	v_mul_f32_e32 v124, 0xbfb8aa3b, v36
	v_mul_f32_e32 v125, 0xbfb8aa3b, v37
	v_mul_f32_e32 v120, 0xbfb8aa3b, v38
	v_mul_f32_e32 v121, 0xbfb8aa3b, v39
	v_pk_mul_f32 v[40:41], v[40:41], v[118:119] op_sel_hi:[1,0]
	v_pk_mul_f32 v[42:43], v[42:43], v[118:119] op_sel_hi:[1,0]
	v_pk_mul_f32 v[32:33], v[32:33], v[118:119] op_sel_hi:[1,0]
	v_pk_mul_f32 v[34:35], v[34:35], v[118:119] op_sel_hi:[1,0]
	v_exp_f32_e32 v152, v152
	v_exp_f32_e32 v153, v153
	v_exp_f32_e32 v148, v148
	v_exp_f32_e32 v149, v149
	v_exp_f32_e32 v124, v124
	v_exp_f32_e32 v125, v125
	v_exp_f32_e32 v120, v120
	v_exp_f32_e32 v121, v121
	v_mad_i64_i32 v[82:83], vcc, v174, s52, v[170:171]
	v_add_f32_e32 v152, 1.0, v152
	v_add_f32_e32 v153, 1.0, v153
	v_add_f32_e32 v148, 1.0, v148
	v_add_f32_e32 v149, 1.0, v149
	v_add_f32_e32 v124, 1.0, v124
	v_add_f32_e32 v125, 1.0, v125
	v_add_f32_e32 v120, 1.0, v120
	v_add_f32_e32 v121, 1.0, v121
	v_rcp_f32_e32 v152, v152
	v_rcp_f32_e32 v153, v153
	v_rcp_f32_e32 v148, v148
	v_rcp_f32_e32 v149, v149
	v_rcp_f32_e32 v124, v124
	v_rcp_f32_e32 v125, v125
	v_rcp_f32_e32 v120, v120
	v_rcp_f32_e32 v121, v121
	s_nop 0
	v_pk_mul_f32 v[44:45], v[44:45], v[152:153]
	v_pk_mul_f32 v[46:47], v[46:47], v[148:149]
	v_pk_mul_f32 v[36:37], v[36:37], v[124:125]
	v_pk_mul_f32 v[38:39], v[38:39], v[120:121]
	v_pk_mul_f32 v[40:41], v[40:41], v[44:45]
	v_pk_mul_f32 v[42:43], v[42:43], v[46:47]
	v_pk_mul_f32 v[32:33], v[32:33], v[36:37]
	v_pk_mul_f32 v[34:35], v[34:35], v[38:39]
	v_cvt_pk_bf16_f32 v40, v40, v41
	v_cvt_pk_bf16_f32 v41, v42, v43
	v_cvt_pk_bf16_f32 v42, v32, v33
	v_cvt_pk_bf16_f32 v43, v34, v35
	global_store_dwordx4 v[82:83], v[40:43], off
	v_pk_mul_f32 v[28:29], v[28:29], v[80:81] op_sel_hi:[1,0]
	v_pk_mul_f32 v[30:31], v[30:31], v[80:81] op_sel_hi:[1,0]
	v_pk_mul_f32 v[20:21], v[20:21], v[80:81] op_sel_hi:[1,0]
	v_pk_mul_f32 v[22:23], v[22:23], v[80:81] op_sel_hi:[1,0]
	v_mul_f32_e32 v152, 0xbfb8aa3b, v28
	v_mul_f32_e32 v153, 0xbfb8aa3b, v29
	v_mul_f32_e32 v148, 0xbfb8aa3b, v30
	v_mul_f32_e32 v149, 0xbfb8aa3b, v31
	v_mul_f32_e32 v124, 0xbfb8aa3b, v20
	v_mul_f32_e32 v125, 0xbfb8aa3b, v21
	v_mul_f32_e32 v120, 0xbfb8aa3b, v22
	v_mul_f32_e32 v121, 0xbfb8aa3b, v23
	v_pk_mul_f32 v[24:25], v[24:25], v[80:81] op_sel_hi:[1,0]
	v_pk_mul_f32 v[26:27], v[26:27], v[80:81] op_sel_hi:[1,0]
	v_pk_mul_f32 v[16:17], v[16:17], v[80:81] op_sel_hi:[1,0]
	v_pk_mul_f32 v[18:19], v[18:19], v[80:81] op_sel_hi:[1,0]
	v_exp_f32_e32 v152, v152
	v_exp_f32_e32 v153, v153
	v_exp_f32_e32 v148, v148
	v_exp_f32_e32 v149, v149
	v_exp_f32_e32 v124, v124
	v_exp_f32_e32 v125, v125
	v_exp_f32_e32 v120, v120
	v_exp_f32_e32 v121, v121
	v_mad_i64_i32 v[82:83], vcc, v172, s52, v[170:171]
	v_add_f32_e32 v152, 1.0, v152
	v_add_f32_e32 v153, 1.0, v153
	v_add_f32_e32 v148, 1.0, v148
	v_add_f32_e32 v149, 1.0, v149
	v_add_f32_e32 v124, 1.0, v124
	v_add_f32_e32 v125, 1.0, v125
	v_add_f32_e32 v120, 1.0, v120
	v_add_f32_e32 v121, 1.0, v121
	v_rcp_f32_e32 v152, v152
	v_rcp_f32_e32 v153, v153
	v_rcp_f32_e32 v148, v148
	v_rcp_f32_e32 v149, v149
	v_rcp_f32_e32 v124, v124
	v_rcp_f32_e32 v125, v125
	v_rcp_f32_e32 v120, v120
	v_rcp_f32_e32 v121, v121
	s_nop 0
	v_pk_mul_f32 v[28:29], v[28:29], v[152:153]
	v_pk_mul_f32 v[30:31], v[30:31], v[148:149]
	v_pk_mul_f32 v[20:21], v[20:21], v[124:125]
	v_pk_mul_f32 v[22:23], v[22:23], v[120:121]
	v_pk_mul_f32 v[24:25], v[24:25], v[28:29]
	v_pk_mul_f32 v[26:27], v[26:27], v[30:31]
	v_pk_mul_f32 v[16:17], v[16:17], v[20:21]
	v_pk_mul_f32 v[18:19], v[18:19], v[22:23]
	v_cvt_pk_bf16_f32 v24, v24, v25
	v_cvt_pk_bf16_f32 v25, v26, v27
	v_cvt_pk_bf16_f32 v26, v16, v17
	v_cvt_pk_bf16_f32 v27, v18, v19
	global_store_dwordx4 v[82:83], v[24:27], off
	v_pk_mul_f32 v[12:13], v[12:13], v[76:77] op_sel_hi:[1,0]
	v_pk_mul_f32 v[14:15], v[14:15], v[76:77] op_sel_hi:[1,0]
	v_pk_mul_f32 v[4:5], v[4:5], v[76:77] op_sel_hi:[1,0]
	v_pk_mul_f32 v[6:7], v[6:7], v[76:77] op_sel_hi:[1,0]
	v_mul_f32_e32 v152, 0xbfb8aa3b, v12
	v_mul_f32_e32 v153, 0xbfb8aa3b, v13
	v_mul_f32_e32 v148, 0xbfb8aa3b, v14
	v_mul_f32_e32 v149, 0xbfb8aa3b, v15
	v_mul_f32_e32 v124, 0xbfb8aa3b, v4
	v_mul_f32_e32 v125, 0xbfb8aa3b, v5
	v_mul_f32_e32 v120, 0xbfb8aa3b, v6
	v_mul_f32_e32 v121, 0xbfb8aa3b, v7
	v_pk_mul_f32 v[8:9], v[8:9], v[76:77] op_sel_hi:[1,0]
	v_pk_mul_f32 v[10:11], v[10:11], v[76:77] op_sel_hi:[1,0]
	v_pk_mul_f32 v[0:1], v[0:1], v[76:77] op_sel_hi:[1,0]
	v_pk_mul_f32 v[2:3], v[2:3], v[76:77] op_sel_hi:[1,0]
	v_exp_f32_e32 v152, v152
	v_exp_f32_e32 v153, v153
	v_exp_f32_e32 v148, v148
	v_exp_f32_e32 v149, v149
	v_exp_f32_e32 v124, v124
	v_exp_f32_e32 v125, v125
	v_exp_f32_e32 v120, v120
	v_exp_f32_e32 v121, v121
	v_mad_i64_i32 v[82:83], vcc, v166, s52, v[170:171]
	v_add_f32_e32 v152, 1.0, v152
	v_add_f32_e32 v153, 1.0, v153
	v_add_f32_e32 v148, 1.0, v148
	v_add_f32_e32 v149, 1.0, v149
	v_add_f32_e32 v124, 1.0, v124
	v_add_f32_e32 v125, 1.0, v125
	v_add_f32_e32 v120, 1.0, v120
	v_add_f32_e32 v121, 1.0, v121
	v_rcp_f32_e32 v152, v152
	v_rcp_f32_e32 v153, v153
	v_rcp_f32_e32 v148, v148
	v_rcp_f32_e32 v149, v149
	v_rcp_f32_e32 v124, v124
	v_rcp_f32_e32 v125, v125
	v_rcp_f32_e32 v120, v120
	v_rcp_f32_e32 v121, v121
	s_nop 0
	v_pk_mul_f32 v[12:13], v[12:13], v[152:153]
	v_pk_mul_f32 v[14:15], v[14:15], v[148:149]
	v_pk_mul_f32 v[4:5], v[4:5], v[124:125]
	v_pk_mul_f32 v[6:7], v[6:7], v[120:121]
	v_pk_mul_f32 v[8:9], v[8:9], v[12:13]
	v_pk_mul_f32 v[10:11], v[10:11], v[14:15]
	v_pk_mul_f32 v[0:1], v[0:1], v[4:5]
	v_pk_mul_f32 v[2:3], v[2:3], v[6:7]
	v_cvt_pk_bf16_f32 v8, v8, v9
	v_cvt_pk_bf16_f32 v9, v10, v11
	v_cvt_pk_bf16_f32 v10, v0, v1
	v_cvt_pk_bf16_f32 v11, v2, v3
	global_store_dwordx4 v[82:83], v[8:11], off
	s_andn2_b64 vcc, exec, s[4:5]
	s_mov_b64 s[6:7], -1
	s_cbranch_vccnz .LBB0_1467
	s_waitcnt vmcnt(0)
	s_andn2_b64 vcc, exec, s[8:9]
	s_cbranch_vccnz .LBB0_1466
	s_barrier
	s_branch .LBB0_1466
